# indexer-score loop: counted wait widened from vmcnt(7) to vmcnt(11) (the four score stores of the previous iteration sit between the needed loads and the wait in the vmcnt queue); preheader waits for
# baseline (speedup 1.0000x reference)
; #define MFMA(a, b, c) __builtin_amdgcn_mfma_f32_32x32x16_bf16((a), (b), (c), 0, 0, 0)
; #define BID opqs((int)blockIdx.x)
; DI void score_phase(const Params& p, char* smem) {
;     ...
;   for (int idx = BID; idx < 512; idx += gridDim.x) {
;     const int half = idx & 1, b = (idx >> 1) & 1, t = idx >> 2;
;     const int blk = (t < 64) ? (127 - t) : (t - 64);
;     const int n = (blk + 1) * 64, ntile = n >> 5;
;     const int nt_lo = half ? (ntile >> 1) : 0, nt_hi = half ? ntile : (ntile >> 1);
;     const int t0 = blk * 64 + wave * 8;
;     const u16* Hb = H + (size_t)b * S_ * HLD;
;     bf16x8 af[4][4];
; #pragma unroll
;     for (int rt = 0; rt < 4; ++rt) {
;       const int tokA = t0 + 2 * rt + ((r >> 2) & 1), head = (r >> 3) * 4 + (r & 3);
; #pragma unroll
;       for (int st = 0; st < 4; ++st) af[rt][st] = *(const bf16x8*)(Hb + (size_t)tokA * HLD + 3072 + head * 64 + st * 16 + 8 * h);
;     }
;     wl[lane] = AUX[(size_t)(b * S_ + t0) * 16 + lane] * 0.125f;
;     wl[64 + lane] = AUX[(size_t)(b * S_ + t0) * 16 + 64 + lane] * 0.125f;
;     __syncthreads();
;     float* scb = SC + (size_t)b * SCB + (size_t)2048 * blk * (blk + 1);
;     bf16x8 bfr[4], bnx[4];
; #pragma unroll
;     for (int st = 0; st < 4; ++st) bfr[st] = *(const bf16x8*)(Hb + (size_t)(nt_lo * 32 + r) * HLD + 4096 + st * 16 + 8 * h);
; #pragma unroll 1
;     for (int nt2 = nt_lo; nt2 < nt_hi; ++nt2) {
;       const int k0 = nt2 * 32;
;       const int kn = (nt2 + 1 < nt_hi) ? (k0 + 32) : k0;
; #pragma unroll
;       for (int st = 0; st < 4; ++st) bnx[st] = *(const bf16x8*)(Hb + (size_t)(kn + r) * HLD + 4096 + st * 16 + 8 * h);
; #pragma unroll
;       for (int rt = 0; rt < 4; ++rt) {
;         f32x16 acc;
; #pragma unroll
;         for (int e = 0; e < 16; ++e) acc[e] = 0.f;
; #pragma unroll
;         for (int st = 0; st < 4; ++st) acc = MFMA(af[rt][st], bfr[st], acc);
.LBB0_820:
	s_ashr_i32 s7, s10, 2
	s_and_b32 s16, s10, 1
	s_bfe_i32 s6, s10, 0x10000
	s_bfe_u32 s8, s10, 0x10001
	s_sub_i32 s9, 0x7f, s7
	s_sub_i32 s15, s7, 64
	s_cmp_lt_i32 s7, 64
	s_cselect_b32 s18, s9, s15
	s_add_i32 s9, s18, 1
	s_and_b32 s15, s6, s9
	s_lshl_b32 s17, s18, 6
	s_mul_i32 s6, s8, 0x5400000
	s_add_u32 s6, s11, s6
	v_add_u32_e32 v2, s17, v198
	s_addc_u32 s7, s12, 0
	v_or_b32_e32 v3, v2, v199
	v_mov_b64_e32 v[4:5], s[6:7]
	s_movk_i32 s22, 0x2a00
	v_mad_i64_i32 v[6:7], s[20:21], v3, s22, v[4:5]
	v_mov_b32_e32 v183, v1
	v_lshl_add_u64 v[6:7], v[6:7], 0, v[182:183]
	v_lshl_add_u64 v[6:7], v[6:7], 0, v[0:1]
	s_mov_b64 s[24:25], 0x1800
	s_movk_i32 s19, 0x1000
	v_lshl_add_u64 v[8:9], v[6:7], 0, s[24:25]
	v_add_co_u32_e32 v6, vcc, s19, v6
	s_lshl_b32 s16, s9, s16
	s_nop 0
	v_addc_co_u32_e32 v7, vcc, 0, v7, vcc
	global_load_dwordx4 v[18:21], v[8:9], off offset:32
	global_load_dwordx4 v[22:25], v[8:9], off offset:64
	global_load_dwordx4 v[26:29], v[6:7], off offset:2048
	global_load_dwordx4 v[30:33], v[8:9], off offset:96
	v_or_b32_e32 v6, 2, v3
	v_mad_i64_i32 v[6:7], s[20:21], v6, s22, v[4:5]
	v_lshl_add_u64 v[6:7], v[6:7], 0, v[182:183]
	v_lshl_add_u64 v[6:7], v[6:7], 0, v[0:1]
	v_lshl_add_u64 v[8:9], v[6:7], 0, s[24:25]
	v_add_co_u32_e32 v6, vcc, s19, v6
	s_cmp_ge_i32 s15, s16
	s_nop 0
	v_addc_co_u32_e32 v7, vcc, 0, v7, vcc
	global_load_dwordx4 v[34:37], v[8:9], off offset:32
	global_load_dwordx4 v[38:41], v[8:9], off offset:64
	global_load_dwordx4 v[42:45], v[6:7], off offset:2048
	global_load_dwordx4 v[46:49], v[8:9], off offset:96
	v_or_b32_e32 v6, 4, v3
	v_mad_i64_i32 v[6:7], s[20:21], v6, s22, v[4:5]
	v_lshl_add_u64 v[6:7], v[6:7], 0, v[182:183]
	v_lshl_add_u64 v[6:7], v[6:7], 0, v[0:1]
	v_lshl_add_u64 v[8:9], v[6:7], 0, s[24:25]
	v_add_co_u32_e32 v6, vcc, s19, v6
	v_or_b32_e32 v3, 6, v3
	s_nop 0
	v_addc_co_u32_e32 v7, vcc, 0, v7, vcc
	global_load_dwordx4 v[50:53], v[8:9], off offset:32
	global_load_dwordx4 v[54:57], v[8:9], off offset:64
	global_load_dwordx4 v[58:61], v[6:7], off offset:2048
	global_load_dwordx4 v[62:65], v[8:9], off offset:96
	v_mad_i64_i32 v[4:5], s[20:21], v3, s22, v[4:5]
	v_lshl_add_u32 v8, s8, 13, v2
	v_lshl_add_u64 v[4:5], v[4:5], 0, v[182:183]
	v_ashrrev_i32_e32 v9, 31, v8
	v_lshl_add_u64 v[4:5], v[4:5], 0, v[0:1]
	v_lshlrev_b64 v[8:9], 6, v[8:9]
	v_lshl_add_u64 v[6:7], v[4:5], 0, s[24:25]
	v_lshl_add_u64 v[8:9], v[180:181], 0, v[8:9]
	v_add_co_u32_e32 v4, vcc, s19, v4
	global_load_dword v3, v[8:9], off
	s_nop 0
	global_load_dword v8, v[8:9], off offset:256
	v_addc_co_u32_e32 v5, vcc, 0, v5, vcc
	global_load_dwordx4 v[66:69], v[6:7], off offset:32
	global_load_dwordx4 v[70:73], v[6:7], off offset:64
	global_load_dwordx4 v[74:77], v[4:5], off offset:2048
	global_load_dwordx4 v[78:81], v[6:7], off offset:96
	s_movk_i32 s23, 0x2000
	s_mov_b64 s[24:25], 0x2000
	s_waitcnt vmcnt(0)
	v_mul_f32_e32 v3, 0x3e000000, v3
	v_mul_f32_e32 v4, 0x3e000000, v8
	ds_write2st64_b32 v200, v3, v4 offset1:1
	s_waitcnt lgkmcnt(0)
	s_barrier
	s_cbranch_scc1 .LBB0_819
	s_mul_i32 s8, s8, 0x8100000
	s_add_u32 s8, s13, s8
	s_mul_hi_i32 s19, s18, s9
	s_mul_i32 s18, s18, s9
	s_addc_u32 s20, s14, 0
	s_lshl_b64 s[18:19], s[18:19], 13
	s_add_u32 s18, s8, s18
	s_addc_u32 s19, s20, s19
	s_lshl_b32 s8, s15, 5
	v_or_b32_e32 v3, s8, v178
	v_mov_b64_e32 v[4:5], s[6:7]
	v_mad_i64_i32 v[4:5], s[20:21], v3, s22, v[4:5]
	v_lshl_add_u64 v[4:5], v[4:5], 0, v[0:1]
	v_lshl_add_u64 v[6:7], v[4:5], 0, s[24:25]
	v_add_co_u32_e32 v4, vcc, s23, v4
	global_load_dwordx4 v[162:165], v[6:7], off offset:96
	s_nop 0
	v_addc_co_u32_e32 v5, vcc, 0, v5, vcc
	global_load_dwordx4 v[174:177], v[4:5], off
	global_load_dwordx4 v[170:173], v[6:7], off offset:32
	global_load_dwordx4 v[166:169], v[6:7], off offset:64
	ds_read_b128 v[82:85], v202
	ds_read_b128 v[86:89], v202 offset:16
	ds_read_b128 v[90:93], v202 offset:32
	ds_read_b128 v[94:97], v202 offset:48
	ds_read_b128 v[98:101], v202 offset:128
	ds_read_b128 v[102:105], v202 offset:144
	ds_read_b128 v[106:109], v202 offset:160
	ds_read_b128 v[110:113], v202 offset:176
	ds_read_b128 v[114:117], v202 offset:256
	ds_read_b128 v[118:121], v202 offset:272
	ds_read_b128 v[122:125], v202 offset:288
	ds_read_b128 v[126:129], v202 offset:304
	ds_read_b128 v[130:133], v202 offset:384
	ds_read_b128 v[134:137], v202 offset:400
	ds_read_b128 v[138:141], v202 offset:416
	ds_read_b128 v[142:145], v202 offset:432
	v_or_b32_e32 v2, v2, v179
	v_subrev_u32_e32 v2, s17, v2
	s_lshl_b32 s9, s9, 6
	v_mov_b32_e32 v185, v1
	v_or_b32_e32 v3, 2, v2
	v_lshl_add_u64 v[186:187], s[18:19], 0, v[184:185]
	v_mad_i64_i32 v[188:189], s[18:19], v2, s9, 0
	v_mad_i64_i32 v[190:191], s[18:19], v3, s9, 0
	v_or_b32_e32 v3, 4, v2
	v_or_b32_e32 v2, 6, v2
	v_mad_i64_i32 v[192:193], s[18:19], v3, s9, 0
	v_mad_i64_i32 v[194:195], s[18:19], v2, s9, 0
	s_add_i32 s19, s8, 32
	s_add_i32 s18, s15, 1
	s_cmp_lt_i32 s18, s16
	s_cselect_b32 s18, s19, s8
	v_or_b32_e32 v244, s18, v178
	v_mov_b64_e32 v[246:247], s[6:7]
	v_mad_i64_i32 v[246:247], s[18:19], v244, s22, v[246:247]
	v_lshl_add_u64 v[246:247], v[246:247], 0, v[0:1]
	v_lshl_add_u64 v[248:249], v[246:247], 0, s[24:25]
	v_add_co_u32_e32 v246, vcc, s23, v246
	s_nop 1
	v_addc_co_u32_e32 v247, vcc, 0, v247, vcc
	global_load_dwordx4 v[154:157], v[246:247], off
	global_load_dwordx4 v[150:153], v[248:249], off offset:32
	global_load_dwordx4 v[146:149], v[248:249], off offset:64
	global_load_dwordx4 v[158:161], v[248:249], off offset:96
	s_waitcnt vmcnt(0) lgkmcnt(0)
	v_mfma_f32_32x32x16_bf16 v[2:17], v[26:29], v[174:177], 0
	v_mfma_f32_32x32x16_bf16 v[2:17], v[18:21], v[170:173], v[2:17]
	v_mfma_f32_32x32x16_bf16 v[2:17], v[22:25], v[166:169], v[2:17]
	v_mfma_f32_32x32x16_bf16 v[2:17], v[30:33], v[162:165], v[2:17]
; #define MFMA(a, b, c) __builtin_amdgcn_mfma_f32_32x32x16_bf16((a), (b), (c), 0, 0, 0)
; DI void score_phase(const Params& p, char* smem) {
;     ...
;     for (int nt2 = nt_lo; nt2 < nt_hi; ++nt2) {
;       const int k0 = nt2 * 32;
;       const int kn = (nt2 + 1 < nt_hi) ? (k0 + 32) : k0;
; #pragma unroll
;       for (int st = 0; st < 4; ++st) bnx[st] = *(const bf16x8*)(Hb + (size_t)(kn + r) * HLD + 4096 + st * 16 + 8 * h);
; #pragma unroll
;       for (int rt = 0; rt < 4; ++rt) {
;         f32x16 acc;
; #pragma unroll
;         for (int e = 0; e < 16; ++e) acc[e] = 0.f;
; #pragma unroll
;         for (int st = 0; st < 4; ++st) acc = MFMA(af[rt][st], bfr[st], acc);
;         float s = 0.f;
; #pragma unroll
;         for (int e4 = 0; e4 < 4; ++e4) {
;           const f32x4 wv = *(const f32x4*)(wl + (2 * rt + h) * 16 + e4 * 4);
; #pragma unroll
;           for (int i = 0; i < 4; ++i) s += fmaxf(acc[e4 * 4 + i], 0.f) * wv[i];
;         }
;         const int row = (t0 + 2 * rt + h) - blk * 64;
;         __builtin_nontemporal_store(s, scb + (size_t)row * n + k0 + r);
;       }
; #pragma unroll
;       for (int st = 0; st < 4; ++st) bfr[st] = bnx[st];
;     }
.LBB0_822:
	s_add_i32 s15, s15, 1
	s_add_i32 s17, s8, 32
	s_add_i32 s19, s8, 64
	s_add_i32 s18, s15, 1
	s_cmp_lt_i32 s18, s16
	s_cselect_b32 s18, s19, s8
	v_or_b32_e32 v244, s18, v178
	v_mov_b64_e32 v[246:247], s[6:7]
	v_mad_i64_i32 v[246:247], s[18:19], v244, s22, v[246:247]
	v_lshl_add_u64 v[246:247], v[246:247], 0, v[0:1]
	v_lshl_add_u64 v[248:249], v[246:247], 0, s[24:25]
	v_add_co_u32_e32 v246, vcc, s23, v246
	s_nop 1
	v_addc_co_u32_e32 v247, vcc, 0, v247, vcc
	global_load_dwordx4 v[204:207], v[246:247], off
	global_load_dwordx4 v[208:211], v[248:249], off offset:32
	global_load_dwordx4 v[212:215], v[248:249], off offset:64
	global_load_dwordx4 v[250:253], v[248:249], off offset:96
	s_ashr_i32 s9, s8, 31
	v_lshl_add_u64 v[196:197], s[8:9], 2, v[186:187]
	s_cmp_ge_i32 s15, s16
	s_mov_b32 s8, s17
	v_mfma_f32_32x32x16_bf16 v[224:239], v[42:45], v[174:177], 0
	v_max_f32_e32 v240, 0, v2
	v_fma_f32 v183, v82, v240, 0
	v_max_f32_e32 v241, 0, v3
	v_fmac_f32_e32 v183, v83, v241
	v_max_f32_e32 v240, 0, v4
	v_fmac_f32_e32 v183, v84, v240
	v_max_f32_e32 v241, 0, v5
	v_fmac_f32_e32 v183, v85, v241
	v_mfma_f32_32x32x16_bf16 v[224:239], v[34:37], v[170:173], v[224:239]
	v_max_f32_e32 v240, 0, v6
	v_fmac_f32_e32 v183, v86, v240
	v_max_f32_e32 v241, 0, v7
	v_fmac_f32_e32 v183, v87, v241
	v_max_f32_e32 v240, 0, v8
	v_fmac_f32_e32 v183, v88, v240
	v_max_f32_e32 v241, 0, v9
	v_fmac_f32_e32 v183, v89, v241
	v_mfma_f32_32x32x16_bf16 v[224:239], v[38:41], v[166:169], v[224:239]
	v_max_f32_e32 v240, 0, v10
	v_fmac_f32_e32 v183, v90, v240
	v_max_f32_e32 v241, 0, v11
	v_fmac_f32_e32 v183, v91, v241
	v_max_f32_e32 v240, 0, v12
	v_fmac_f32_e32 v183, v92, v240
	v_max_f32_e32 v241, 0, v13
	v_fmac_f32_e32 v183, v93, v241
	v_mfma_f32_32x32x16_bf16 v[224:239], v[46:49], v[162:165], v[224:239]
	v_max_f32_e32 v240, 0, v14
	v_fmac_f32_e32 v183, v94, v240
	v_max_f32_e32 v241, 0, v15
	v_fmac_f32_e32 v183, v95, v241
	v_max_f32_e32 v240, 0, v16
	v_fmac_f32_e32 v183, v96, v240
	v_max_f32_e32 v241, 0, v17
	v_fmac_f32_e32 v183, v97, v241
	v_lshl_add_u64 v[242:243], v[188:189], 2, v[196:197]
	global_store_dword v[242:243], v183, off nt
	s_nop 1
	v_mfma_f32_32x32x16_bf16 v[2:17], v[58:61], v[174:177], 0
	v_max_f32_e32 v240, 0, v224
	v_fma_f32 v183, v98, v240, 0
	v_max_f32_e32 v241, 0, v225
	v_fmac_f32_e32 v183, v99, v241
	v_max_f32_e32 v240, 0, v226
	v_fmac_f32_e32 v183, v100, v240
	v_max_f32_e32 v241, 0, v227
	v_fmac_f32_e32 v183, v101, v241
	v_mfma_f32_32x32x16_bf16 v[2:17], v[50:53], v[170:173], v[2:17]
	v_max_f32_e32 v240, 0, v228
	v_fmac_f32_e32 v183, v102, v240
	v_max_f32_e32 v241, 0, v229
	v_fmac_f32_e32 v183, v103, v241
	v_max_f32_e32 v240, 0, v230
	v_fmac_f32_e32 v183, v104, v240
	v_max_f32_e32 v241, 0, v231
	v_fmac_f32_e32 v183, v105, v241
	v_mfma_f32_32x32x16_bf16 v[2:17], v[54:57], v[166:169], v[2:17]
	v_max_f32_e32 v240, 0, v232
	v_fmac_f32_e32 v183, v106, v240
	v_max_f32_e32 v241, 0, v233
	v_fmac_f32_e32 v183, v107, v241
	v_max_f32_e32 v240, 0, v234
	v_fmac_f32_e32 v183, v108, v240
	v_max_f32_e32 v241, 0, v235
	v_fmac_f32_e32 v183, v109, v241
	v_mfma_f32_32x32x16_bf16 v[2:17], v[62:65], v[162:165], v[2:17]
	v_max_f32_e32 v240, 0, v236
	v_fmac_f32_e32 v183, v110, v240
	v_max_f32_e32 v241, 0, v237
	v_fmac_f32_e32 v183, v111, v241
	v_max_f32_e32 v240, 0, v238
	v_fmac_f32_e32 v183, v112, v240
	v_max_f32_e32 v241, 0, v239
	v_fmac_f32_e32 v183, v113, v241
	v_lshl_add_u64 v[242:243], v[190:191], 2, v[196:197]
	global_store_dword v[242:243], v183, off nt
	s_nop 1
	v_mfma_f32_32x32x16_bf16 v[224:239], v[74:77], v[174:177], 0
	v_max_f32_e32 v240, 0, v2
	v_fma_f32 v183, v114, v240, 0
	v_max_f32_e32 v241, 0, v3
	v_fmac_f32_e32 v183, v115, v241
	v_max_f32_e32 v240, 0, v4
	v_fmac_f32_e32 v183, v116, v240
	v_max_f32_e32 v241, 0, v5
	v_fmac_f32_e32 v183, v117, v241
	v_mfma_f32_32x32x16_bf16 v[224:239], v[66:69], v[170:173], v[224:239]
	v_max_f32_e32 v240, 0, v6
	v_fmac_f32_e32 v183, v118, v240
	v_max_f32_e32 v241, 0, v7
	v_fmac_f32_e32 v183, v119, v241
	v_max_f32_e32 v240, 0, v8
	v_fmac_f32_e32 v183, v120, v240
	v_max_f32_e32 v241, 0, v9
	v_fmac_f32_e32 v183, v121, v241
	v_mfma_f32_32x32x16_bf16 v[224:239], v[70:73], v[166:169], v[224:239]
	v_max_f32_e32 v240, 0, v10
	v_fmac_f32_e32 v183, v122, v240
	v_max_f32_e32 v241, 0, v11
	v_fmac_f32_e32 v183, v123, v241
	v_max_f32_e32 v240, 0, v12
	v_fmac_f32_e32 v183, v124, v240
	v_max_f32_e32 v241, 0, v13
	v_fmac_f32_e32 v183, v125, v241
	v_mfma_f32_32x32x16_bf16 v[224:239], v[78:81], v[162:165], v[224:239]
	v_max_f32_e32 v240, 0, v14
	v_fmac_f32_e32 v183, v126, v240
	v_max_f32_e32 v241, 0, v15
	v_fmac_f32_e32 v183, v127, v241
	v_max_f32_e32 v240, 0, v16
	v_fmac_f32_e32 v183, v128, v240
	v_max_f32_e32 v241, 0, v17
	v_fmac_f32_e32 v183, v129, v241
	v_lshl_add_u64 v[242:243], v[192:193], 2, v[196:197]
	global_store_dword v[242:243], v183, off nt
	s_nop 1
	s_waitcnt vmcnt(11)
	v_mfma_f32_32x32x16_bf16 v[2:17], v[26:29], v[154:157], 0
	v_max_f32_e32 v240, 0, v224
	v_fma_f32 v183, v130, v240, 0
	v_max_f32_e32 v241, 0, v225
	v_fmac_f32_e32 v183, v131, v241
	v_max_f32_e32 v240, 0, v226
	v_fmac_f32_e32 v183, v132, v240
	v_max_f32_e32 v241, 0, v227
	v_fmac_f32_e32 v183, v133, v241
	v_mfma_f32_32x32x16_bf16 v[2:17], v[18:21], v[150:153], v[2:17]
	v_max_f32_e32 v240, 0, v228
	v_fmac_f32_e32 v183, v134, v240
	v_max_f32_e32 v241, 0, v229
	v_fmac_f32_e32 v183, v135, v241
	v_max_f32_e32 v240, 0, v230
	v_fmac_f32_e32 v183, v136, v240
	v_max_f32_e32 v241, 0, v231
	v_fmac_f32_e32 v183, v137, v241
	v_mfma_f32_32x32x16_bf16 v[2:17], v[22:25], v[146:149], v[2:17]
	v_max_f32_e32 v240, 0, v232
	v_fmac_f32_e32 v183, v138, v240
	v_max_f32_e32 v241, 0, v233
	v_fmac_f32_e32 v183, v139, v241
	v_max_f32_e32 v240, 0, v234
	v_fmac_f32_e32 v183, v140, v240
	v_max_f32_e32 v241, 0, v235
	v_fmac_f32_e32 v183, v141, v241
	v_mfma_f32_32x32x16_bf16 v[2:17], v[30:33], v[158:161], v[2:17]
	v_max_f32_e32 v240, 0, v236
	v_fmac_f32_e32 v183, v142, v240
	v_max_f32_e32 v241, 0, v237
	v_fmac_f32_e32 v183, v143, v241
	v_max_f32_e32 v240, 0, v238
	v_fmac_f32_e32 v183, v144, v240
	v_max_f32_e32 v241, 0, v239
	v_fmac_f32_e32 v183, v145, v241
	v_lshl_add_u64 v[242:243], v[194:195], 2, v[196:197]
	global_store_dword v[242:243], v183, off nt
	s_nop 1
	s_cbranch_scc1 .LBB0_819
; #define MFMA(a, b, c) __builtin_amdgcn_mfma_f32_32x32x16_bf16((a), (b), (c), 0, 0, 0)
; DI void score_phase(const Params& p, char* smem) {
;     ...
;     for (int nt2 = nt_lo; nt2 < nt_hi; ++nt2) {
;       const int k0 = nt2 * 32;
;       const int kn = (nt2 + 1 < nt_hi) ? (k0 + 32) : k0;
; #pragma unroll
;       for (int st = 0; st < 4; ++st) bnx[st] = *(const bf16x8*)(Hb + (size_t)(kn + r) * HLD + 4096 + st * 16 + 8 * h);
; #pragma unroll
;       for (int rt = 0; rt < 4; ++rt) {
;         f32x16 acc;
; #pragma unroll
;         for (int e = 0; e < 16; ++e) acc[e] = 0.f;
; #pragma unroll
;         for (int st = 0; st < 4; ++st) acc = MFMA(af[rt][st], bfr[st], acc);
;         float s = 0.f;
; #pragma unroll
;         for (int e4 = 0; e4 < 4; ++e4) {
;           const f32x4 wv = *(const f32x4*)(wl + (2 * rt + h) * 16 + e4 * 4);
; #pragma unroll
;           for (int i = 0; i < 4; ++i) s += fmaxf(acc[e4 * 4 + i], 0.f) * wv[i];
;         }
;         const int row = (t0 + 2 * rt + h) - blk * 64;
;         __builtin_nontemporal_store(s, scb + (size_t)row * n + k0 + r);
;       }
; #pragma unroll
;       for (int st = 0; st < 4; ++st) bfr[st] = bnx[st];
;     }
	s_add_i32 s15, s15, 1
	s_add_i32 s17, s8, 32
	s_add_i32 s19, s8, 64
	s_add_i32 s18, s15, 1
	s_cmp_lt_i32 s18, s16
	s_cselect_b32 s18, s19, s8
	v_or_b32_e32 v244, s18, v178
	v_mov_b64_e32 v[246:247], s[6:7]
	v_mad_i64_i32 v[246:247], s[18:19], v244, s22, v[246:247]
	v_lshl_add_u64 v[246:247], v[246:247], 0, v[0:1]
	v_lshl_add_u64 v[248:249], v[246:247], 0, s[24:25]
	v_add_co_u32_e32 v246, vcc, s23, v246
	s_nop 1
	v_addc_co_u32_e32 v247, vcc, 0, v247, vcc
	global_load_dwordx4 v[174:177], v[246:247], off
	global_load_dwordx4 v[170:173], v[248:249], off offset:32
	global_load_dwordx4 v[166:169], v[248:249], off offset:64
	global_load_dwordx4 v[162:165], v[248:249], off offset:96
	s_ashr_i32 s9, s8, 31
	v_lshl_add_u64 v[196:197], s[8:9], 2, v[186:187]
	s_cmp_ge_i32 s15, s16
	s_mov_b32 s8, s17
	v_mfma_f32_32x32x16_bf16 v[224:239], v[42:45], v[154:157], 0
	v_max_f32_e32 v240, 0, v2
	v_fma_f32 v183, v82, v240, 0
	v_max_f32_e32 v241, 0, v3
	v_fmac_f32_e32 v183, v83, v241
	v_max_f32_e32 v240, 0, v4
	v_fmac_f32_e32 v183, v84, v240
	v_max_f32_e32 v241, 0, v5
	v_fmac_f32_e32 v183, v85, v241
	v_mfma_f32_32x32x16_bf16 v[224:239], v[34:37], v[150:153], v[224:239]
	v_max_f32_e32 v240, 0, v6
	v_fmac_f32_e32 v183, v86, v240
	v_max_f32_e32 v241, 0, v7
	v_fmac_f32_e32 v183, v87, v241
	v_max_f32_e32 v240, 0, v8
	v_fmac_f32_e32 v183, v88, v240
	v_max_f32_e32 v241, 0, v9
	v_fmac_f32_e32 v183, v89, v241
	v_mfma_f32_32x32x16_bf16 v[224:239], v[38:41], v[146:149], v[224:239]
	v_max_f32_e32 v240, 0, v10
	v_fmac_f32_e32 v183, v90, v240
	v_max_f32_e32 v241, 0, v11
	v_fmac_f32_e32 v183, v91, v241
	v_max_f32_e32 v240, 0, v12
	v_fmac_f32_e32 v183, v92, v240
	v_max_f32_e32 v241, 0, v13
	v_fmac_f32_e32 v183, v93, v241
	v_mfma_f32_32x32x16_bf16 v[224:239], v[46:49], v[158:161], v[224:239]
	v_max_f32_e32 v240, 0, v14
	v_fmac_f32_e32 v183, v94, v240
	v_max_f32_e32 v241, 0, v15
	v_fmac_f32_e32 v183, v95, v241
	v_max_f32_e32 v240, 0, v16
	v_fmac_f32_e32 v183, v96, v240
	v_max_f32_e32 v241, 0, v17
	v_fmac_f32_e32 v183, v97, v241
	v_lshl_add_u64 v[242:243], v[188:189], 2, v[196:197]
	global_store_dword v[242:243], v183, off nt
	s_nop 1
	v_mfma_f32_32x32x16_bf16 v[2:17], v[58:61], v[154:157], 0
	v_max_f32_e32 v240, 0, v224
	v_fma_f32 v183, v98, v240, 0
	v_max_f32_e32 v241, 0, v225
	v_fmac_f32_e32 v183, v99, v241
	v_max_f32_e32 v240, 0, v226
	v_fmac_f32_e32 v183, v100, v240
	v_max_f32_e32 v241, 0, v227
	v_fmac_f32_e32 v183, v101, v241
	v_mfma_f32_32x32x16_bf16 v[2:17], v[50:53], v[150:153], v[2:17]
	v_max_f32_e32 v240, 0, v228
	v_fmac_f32_e32 v183, v102, v240
	v_max_f32_e32 v241, 0, v229
	v_fmac_f32_e32 v183, v103, v241
	v_max_f32_e32 v240, 0, v230
	v_fmac_f32_e32 v183, v104, v240
	v_max_f32_e32 v241, 0, v231
	v_fmac_f32_e32 v183, v105, v241
	v_mfma_f32_32x32x16_bf16 v[2:17], v[54:57], v[146:149], v[2:17]
	v_max_f32_e32 v240, 0, v232
	v_fmac_f32_e32 v183, v106, v240
	v_max_f32_e32 v241, 0, v233
	v_fmac_f32_e32 v183, v107, v241
	v_max_f32_e32 v240, 0, v234
	v_fmac_f32_e32 v183, v108, v240
	v_max_f32_e32 v241, 0, v235
	v_fmac_f32_e32 v183, v109, v241
	v_mfma_f32_32x32x16_bf16 v[2:17], v[62:65], v[158:161], v[2:17]
	v_max_f32_e32 v240, 0, v236
	v_fmac_f32_e32 v183, v110, v240
	v_max_f32_e32 v241, 0, v237
	v_fmac_f32_e32 v183, v111, v241
	v_max_f32_e32 v240, 0, v238
	v_fmac_f32_e32 v183, v112, v240
	v_max_f32_e32 v241, 0, v239
	v_fmac_f32_e32 v183, v113, v241
	v_lshl_add_u64 v[242:243], v[190:191], 2, v[196:197]
	global_store_dword v[242:243], v183, off nt
	s_nop 1
	v_mfma_f32_32x32x16_bf16 v[224:239], v[74:77], v[154:157], 0
	v_max_f32_e32 v240, 0, v2
	v_fma_f32 v183, v114, v240, 0
	v_max_f32_e32 v241, 0, v3
	v_fmac_f32_e32 v183, v115, v241
	v_max_f32_e32 v240, 0, v4
	v_fmac_f32_e32 v183, v116, v240
	v_max_f32_e32 v241, 0, v5
	v_fmac_f32_e32 v183, v117, v241
	v_mfma_f32_32x32x16_bf16 v[224:239], v[66:69], v[150:153], v[224:239]
	v_max_f32_e32 v240, 0, v6
	v_fmac_f32_e32 v183, v118, v240
	v_max_f32_e32 v241, 0, v7
	v_fmac_f32_e32 v183, v119, v241
	v_max_f32_e32 v240, 0, v8
	v_fmac_f32_e32 v183, v120, v240
	v_max_f32_e32 v241, 0, v9
	v_fmac_f32_e32 v183, v121, v241
	v_mfma_f32_32x32x16_bf16 v[224:239], v[70:73], v[146:149], v[224:239]
	v_max_f32_e32 v240, 0, v10
	v_fmac_f32_e32 v183, v122, v240
	v_max_f32_e32 v241, 0, v11
	v_fmac_f32_e32 v183, v123, v241
	v_max_f32_e32 v240, 0, v12
	v_fmac_f32_e32 v183, v124, v240
	v_max_f32_e32 v241, 0, v13
	v_fmac_f32_e32 v183, v125, v241
	v_mfma_f32_32x32x16_bf16 v[224:239], v[78:81], v[158:161], v[224:239]
	v_max_f32_e32 v240, 0, v14
	v_fmac_f32_e32 v183, v126, v240
	v_max_f32_e32 v241, 0, v15
	v_fmac_f32_e32 v183, v127, v241
	v_max_f32_e32 v240, 0, v16
	v_fmac_f32_e32 v183, v128, v240
	v_max_f32_e32 v241, 0, v17
	v_fmac_f32_e32 v183, v129, v241
	v_lshl_add_u64 v[242:243], v[192:193], 2, v[196:197]
	global_store_dword v[242:243], v183, off nt
	s_nop 1
	s_waitcnt vmcnt(11)
	v_mfma_f32_32x32x16_bf16 v[2:17], v[26:29], v[204:207], 0
	v_max_f32_e32 v240, 0, v224
	v_fma_f32 v183, v130, v240, 0
	v_max_f32_e32 v241, 0, v225
	v_fmac_f32_e32 v183, v131, v241
	v_max_f32_e32 v240, 0, v226
	v_fmac_f32_e32 v183, v132, v240
	v_max_f32_e32 v241, 0, v227
	v_fmac_f32_e32 v183, v133, v241
	v_mfma_f32_32x32x16_bf16 v[2:17], v[18:21], v[208:211], v[2:17]
	v_max_f32_e32 v240, 0, v228
	v_fmac_f32_e32 v183, v134, v240
	v_max_f32_e32 v241, 0, v229
	v_fmac_f32_e32 v183, v135, v241
	v_max_f32_e32 v240, 0, v230
	v_fmac_f32_e32 v183, v136, v240
	v_max_f32_e32 v241, 0, v231
	v_fmac_f32_e32 v183, v137, v241
	v_mfma_f32_32x32x16_bf16 v[2:17], v[22:25], v[212:215], v[2:17]
	v_max_f32_e32 v240, 0, v232
	v_fmac_f32_e32 v183, v138, v240
	v_max_f32_e32 v241, 0, v233
	v_fmac_f32_e32 v183, v139, v241
	v_max_f32_e32 v240, 0, v234
	v_fmac_f32_e32 v183, v140, v240
	v_max_f32_e32 v241, 0, v235
	v_fmac_f32_e32 v183, v141, v241
	v_mfma_f32_32x32x16_bf16 v[2:17], v[30:33], v[250:253], v[2:17]
	v_max_f32_e32 v240, 0, v236
	v_fmac_f32_e32 v183, v142, v240
	v_max_f32_e32 v241, 0, v237
	v_fmac_f32_e32 v183, v143, v241
	v_max_f32_e32 v240, 0, v238
	v_fmac_f32_e32 v183, v144, v240
	v_max_f32_e32 v241, 0, v239
	v_fmac_f32_e32 v183, v145, v241
	v_lshl_add_u64 v[242:243], v[194:195], 2, v[196:197]
	global_store_dword v[242:243], v183, off nt
	s_nop 1
	s_cbranch_scc1 .LBB0_819
; #define MFMA(a, b, c) __builtin_amdgcn_mfma_f32_32x32x16_bf16((a), (b), (c), 0, 0, 0)
; DI void score_phase(const Params& p, char* smem) {
;     ...
;     for (int nt2 = nt_lo; nt2 < nt_hi; ++nt2) {
;       const int k0 = nt2 * 32;
;       const int kn = (nt2 + 1 < nt_hi) ? (k0 + 32) : k0;
; #pragma unroll
;       for (int st = 0; st < 4; ++st) bnx[st] = *(const bf16x8*)(Hb + (size_t)(kn + r) * HLD + 4096 + st * 16 + 8 * h);
; #pragma unroll
;       for (int rt = 0; rt < 4; ++rt) {
;         f32x16 acc;
; #pragma unroll
;         for (int e = 0; e < 16; ++e) acc[e] = 0.f;
; #pragma unroll
;         for (int st = 0; st < 4; ++st) acc = MFMA(af[rt][st], bfr[st], acc);
;         float s = 0.f;
; #pragma unroll
;         for (int e4 = 0; e4 < 4; ++e4) {
;           const f32x4 wv = *(const f32x4*)(wl + (2 * rt + h) * 16 + e4 * 4);
; #pragma unroll
;           for (int i = 0; i < 4; ++i) s += fmaxf(acc[e4 * 4 + i], 0.f) * wv[i];
;         }
;         const int row = (t0 + 2 * rt + h) - blk * 64;
;         __builtin_nontemporal_store(s, scb + (size_t)row * n + k0 + r);
;       }
; #pragma unroll
;       for (int st = 0; st < 4; ++st) bfr[st] = bnx[st];
;     }
	s_add_i32 s15, s15, 1
	s_add_i32 s17, s8, 32
	s_add_i32 s19, s8, 64
	s_add_i32 s18, s15, 1
	s_cmp_lt_i32 s18, s16
	s_cselect_b32 s18, s19, s8
	v_or_b32_e32 v244, s18, v178
	v_mov_b64_e32 v[246:247], s[6:7]
	v_mad_i64_i32 v[246:247], s[18:19], v244, s22, v[246:247]
	v_lshl_add_u64 v[246:247], v[246:247], 0, v[0:1]
	v_lshl_add_u64 v[248:249], v[246:247], 0, s[24:25]
	v_add_co_u32_e32 v246, vcc, s23, v246
	s_nop 1
	v_addc_co_u32_e32 v247, vcc, 0, v247, vcc
	global_load_dwordx4 v[154:157], v[246:247], off
	global_load_dwordx4 v[150:153], v[248:249], off offset:32
	global_load_dwordx4 v[146:149], v[248:249], off offset:64
	global_load_dwordx4 v[158:161], v[248:249], off offset:96
	s_ashr_i32 s9, s8, 31
	v_lshl_add_u64 v[196:197], s[8:9], 2, v[186:187]
	s_cmp_ge_i32 s15, s16
	s_mov_b32 s8, s17
	v_mfma_f32_32x32x16_bf16 v[224:239], v[42:45], v[204:207], 0
	v_max_f32_e32 v240, 0, v2
	v_fma_f32 v183, v82, v240, 0
	v_max_f32_e32 v241, 0, v3
	v_fmac_f32_e32 v183, v83, v241
	v_max_f32_e32 v240, 0, v4
	v_fmac_f32_e32 v183, v84, v240
	v_max_f32_e32 v241, 0, v5
	v_fmac_f32_e32 v183, v85, v241
	v_mfma_f32_32x32x16_bf16 v[224:239], v[34:37], v[208:211], v[224:239]
	v_max_f32_e32 v240, 0, v6
	v_fmac_f32_e32 v183, v86, v240
	v_max_f32_e32 v241, 0, v7
	v_fmac_f32_e32 v183, v87, v241
	v_max_f32_e32 v240, 0, v8
	v_fmac_f32_e32 v183, v88, v240
	v_max_f32_e32 v241, 0, v9
	v_fmac_f32_e32 v183, v89, v241
	v_mfma_f32_32x32x16_bf16 v[224:239], v[38:41], v[212:215], v[224:239]
	v_max_f32_e32 v240, 0, v10
	v_fmac_f32_e32 v183, v90, v240
	v_max_f32_e32 v241, 0, v11
	v_fmac_f32_e32 v183, v91, v241
	v_max_f32_e32 v240, 0, v12
	v_fmac_f32_e32 v183, v92, v240
	v_max_f32_e32 v241, 0, v13
	v_fmac_f32_e32 v183, v93, v241
	v_mfma_f32_32x32x16_bf16 v[224:239], v[46:49], v[250:253], v[224:239]
	v_max_f32_e32 v240, 0, v14
	v_fmac_f32_e32 v183, v94, v240
	v_max_f32_e32 v241, 0, v15
	v_fmac_f32_e32 v183, v95, v241
	v_max_f32_e32 v240, 0, v16
	v_fmac_f32_e32 v183, v96, v240
	v_max_f32_e32 v241, 0, v17
	v_fmac_f32_e32 v183, v97, v241
	v_lshl_add_u64 v[242:243], v[188:189], 2, v[196:197]
	global_store_dword v[242:243], v183, off nt
	s_nop 1
	v_mfma_f32_32x32x16_bf16 v[2:17], v[58:61], v[204:207], 0
	v_max_f32_e32 v240, 0, v224
	v_fma_f32 v183, v98, v240, 0
	v_max_f32_e32 v241, 0, v225
	v_fmac_f32_e32 v183, v99, v241
	v_max_f32_e32 v240, 0, v226
	v_fmac_f32_e32 v183, v100, v240
	v_max_f32_e32 v241, 0, v227
	v_fmac_f32_e32 v183, v101, v241
	v_mfma_f32_32x32x16_bf16 v[2:17], v[50:53], v[208:211], v[2:17]
	v_max_f32_e32 v240, 0, v228
	v_fmac_f32_e32 v183, v102, v240
	v_max_f32_e32 v241, 0, v229
	v_fmac_f32_e32 v183, v103, v241
	v_max_f32_e32 v240, 0, v230
	v_fmac_f32_e32 v183, v104, v240
	v_max_f32_e32 v241, 0, v231
	v_fmac_f32_e32 v183, v105, v241
	v_mfma_f32_32x32x16_bf16 v[2:17], v[54:57], v[212:215], v[2:17]
	v_max_f32_e32 v240, 0, v232
	v_fmac_f32_e32 v183, v106, v240
	v_max_f32_e32 v241, 0, v233
	v_fmac_f32_e32 v183, v107, v241
	v_max_f32_e32 v240, 0, v234
	v_fmac_f32_e32 v183, v108, v240
	v_max_f32_e32 v241, 0, v235
	v_fmac_f32_e32 v183, v109, v241
	v_mfma_f32_32x32x16_bf16 v[2:17], v[62:65], v[250:253], v[2:17]
	v_max_f32_e32 v240, 0, v236
	v_fmac_f32_e32 v183, v110, v240
	v_max_f32_e32 v241, 0, v237
	v_fmac_f32_e32 v183, v111, v241
	v_max_f32_e32 v240, 0, v238
	v_fmac_f32_e32 v183, v112, v240
	v_max_f32_e32 v241, 0, v239
	v_fmac_f32_e32 v183, v113, v241
	v_lshl_add_u64 v[242:243], v[190:191], 2, v[196:197]
	global_store_dword v[242:243], v183, off nt
	s_nop 1
	v_mfma_f32_32x32x16_bf16 v[224:239], v[74:77], v[204:207], 0
	v_max_f32_e32 v240, 0, v2
	v_fma_f32 v183, v114, v240, 0
	v_max_f32_e32 v241, 0, v3
	v_fmac_f32_e32 v183, v115, v241
	v_max_f32_e32 v240, 0, v4
	v_fmac_f32_e32 v183, v116, v240
	v_max_f32_e32 v241, 0, v5
	v_fmac_f32_e32 v183, v117, v241
	v_mfma_f32_32x32x16_bf16 v[224:239], v[66:69], v[208:211], v[224:239]
	v_max_f32_e32 v240, 0, v6
	v_fmac_f32_e32 v183, v118, v240
	v_max_f32_e32 v241, 0, v7
	v_fmac_f32_e32 v183, v119, v241
	v_max_f32_e32 v240, 0, v8
	v_fmac_f32_e32 v183, v120, v240
	v_max_f32_e32 v241, 0, v9
	v_fmac_f32_e32 v183, v121, v241
	v_mfma_f32_32x32x16_bf16 v[224:239], v[70:73], v[212:215], v[224:239]
	v_max_f32_e32 v240, 0, v10
	v_fmac_f32_e32 v183, v122, v240
	v_max_f32_e32 v241, 0, v11
	v_fmac_f32_e32 v183, v123, v241
	v_max_f32_e32 v240, 0, v12
	v_fmac_f32_e32 v183, v124, v240
	v_max_f32_e32 v241, 0, v13
	v_fmac_f32_e32 v183, v125, v241
	v_mfma_f32_32x32x16_bf16 v[224:239], v[78:81], v[250:253], v[224:239]
	v_max_f32_e32 v240, 0, v14
	v_fmac_f32_e32 v183, v126, v240
	v_max_f32_e32 v241, 0, v15
	v_fmac_f32_e32 v183, v127, v241
	v_max_f32_e32 v240, 0, v16
	v_fmac_f32_e32 v183, v128, v240
	v_max_f32_e32 v241, 0, v17
	v_fmac_f32_e32 v183, v129, v241
	v_lshl_add_u64 v[242:243], v[192:193], 2, v[196:197]
	global_store_dword v[242:243], v183, off nt
	s_nop 1
	s_waitcnt vmcnt(11)
	v_mfma_f32_32x32x16_bf16 v[2:17], v[26:29], v[174:177], 0
	v_max_f32_e32 v240, 0, v224
	v_fma_f32 v183, v130, v240, 0
	v_max_f32_e32 v241, 0, v225
	v_fmac_f32_e32 v183, v131, v241
	v_max_f32_e32 v240, 0, v226
	v_fmac_f32_e32 v183, v132, v240
	v_max_f32_e32 v241, 0, v227
	v_fmac_f32_e32 v183, v133, v241
	v_mfma_f32_32x32x16_bf16 v[2:17], v[18:21], v[170:173], v[2:17]
	v_max_f32_e32 v240, 0, v228
	v_fmac_f32_e32 v183, v134, v240
	v_max_f32_e32 v241, 0, v229
	v_fmac_f32_e32 v183, v135, v241
	v_max_f32_e32 v240, 0, v230
	v_fmac_f32_e32 v183, v136, v240
	v_max_f32_e32 v241, 0, v231
	v_fmac_f32_e32 v183, v137, v241
	v_mfma_f32_32x32x16_bf16 v[2:17], v[22:25], v[166:169], v[2:17]
	v_max_f32_e32 v240, 0, v232
	v_fmac_f32_e32 v183, v138, v240
	v_max_f32_e32 v241, 0, v233
	v_fmac_f32_e32 v183, v139, v241
	v_max_f32_e32 v240, 0, v234
	v_fmac_f32_e32 v183, v140, v240
	v_max_f32_e32 v241, 0, v235
	v_fmac_f32_e32 v183, v141, v241
	v_mfma_f32_32x32x16_bf16 v[2:17], v[30:33], v[162:165], v[2:17]
	v_max_f32_e32 v240, 0, v236
	v_fmac_f32_e32 v183, v142, v240
	v_max_f32_e32 v241, 0, v237
	v_fmac_f32_e32 v183, v143, v241
	v_max_f32_e32 v240, 0, v238
	v_fmac_f32_e32 v183, v144, v240
	v_max_f32_e32 v241, 0, v239
	v_fmac_f32_e32 v183, v145, v241
	v_lshl_add_u64 v[242:243], v[194:195], 2, v[196:197]
	global_store_dword v[242:243], v183, off nt
	s_nop 1
	s_cbranch_scc0 .LBB0_822
	s_branch .LBB0_819
